# in-proj rounds column-major within the XCD (round 0: column tiles 0-5, round 1: 5-10) to shrink the per-round L2 working set; heavy-epilogue tiles all in round 1
# baseline (speedup 1.0000x reference)
.Lmy_rank_skip:
	s_or_b64 exec, exec, s[60:61]
	s_waitcnt vmcnt(0) lgkmcnt(0)
	s_barrier
	v_mov_b32_e32 v1, 0x20040
	ds_read_b32 v1, v1
	v_readfirstlane_b32 s58, v0
	s_waitcnt lgkmcnt(0)
	v_readfirstlane_b32 s59, v1
	s_lshl_b32 s59, s59, 3
	s_add_i32 s59, s59, s71
	s_cmp_eq_u32 s58, 0
	s_cselect_b32 s2, s59, s2
	s_cselect_b32 s58, 1, 0
	s_nop 0
	v_writelane_b32 v255, s58, 46
	v_writelane_b32 v255, s2, 47
	s_ashr_i32 s43, s2, 31
	s_lshr_b32 s0, s43, 29
	s_add_i32 s0, s2, s0
	s_and_b32 s1, s0, -8
	s_sub_i32 s1, s2, s1
	s_add_i32 s4, s76, 0xfffffa00
	s_cmp_lt_i32 s1, 0
	s_movk_i32 s7, 0x61
	s_cselect_b32 s5, 45, 44
	s_cselect_b32 s6, 25, 24
	s_cselect_b32 s7, s7, 0x60
	s_cmpk_gt_i32 s42, 0xc0
	s_cselect_b32 s33, s4, s76
	s_add_i32 s4, s42, 0xffffff40
	s_cmpk_gt_i32 s42, 0xc0
	s_cselect_b32 s63, s4, s42
	s_add_i32 s4, s2, 0xffffff40
	s_mov_b32 s8, s76
	s_cmpk_gt_i32 s42, 0xc0
	v_writelane_b32 v254, s8, 17
	s_cselect_b32 s13, s4, s2
	s_cmpk_lt_i32 s2, 0x200
	v_writelane_b32 v254, s9, 18
	s_cselect_b64 s[8:9], -1, 0
	v_writelane_b32 v254, s8, 19
	s_add_i32 s4, s2, 0xa0
	s_bfe_u32 s4, s4, 0x50003
	v_writelane_b32 v254, s9, 20
	s_and_b32 s8, s2, 7
	s_mul_i32 s8, s8, 20
	s_add_i32 s4, s4, s8
	s_mul_i32 s8, s4, 0xcd
	s_bfe_u32 s8, s8, 0x3000d
	s_mul_i32 s9, s8, 40
	s_mul_i32 s5, s5, s1
	s_sub_i32 s9, s4, s9
	s_ashr_i32 s4, s0, 3
	s_add_i32 s5, s5, s4
	s_mul_hi_i32 s0, s5, 0x2e8ba2e9
	s_lshr_b32 s11, s0, 31
	s_ashr_i32 s0, s0, 4
	s_add_i32 s0, s0, s11
	s_mul_i32 s11, s0, 0x58
	s_sub_i32 s5, s5, s11
	s_bfe_i32 s11, s5, 0x80000
	s_bfe_u32 s11, s11, 0x3000c
	s_add_i32 s11, s5, s11
	s_bfe_i32 s12, s11, 0x80000
	s_and_b32 s11, s11, 0xf8
	s_lshl_b32 s8, s8, 2
	s_sub_i32 s5, s5, s11
	s_and_b32 s10, s8, 28
	s_lshl_b32 s0, s0, 3
	s_sext_i32_i8 s5, s5
	s_sub_i32 s10, 16, s10
	s_sext_i32_i16 s12, s12
	s_add_i32 s0, s0, s5
	s_min_u32 s10, s10, 4
	s_ashr_i32 s11, s12, 3
	s_add_i32 s0, s0, 16
	s_ashr_i32 s51, s42, 31
	s_add_u32 s48, s38, 0x4820000
	s_addc_u32 s49, s39, 0
	s_add_u32 s50, s38, 0x3820000
	s_addc_u32 s68, s39, 0
	s_add_u32 s69, s38, 0x5820000
	s_addc_u32 s62, s39, 0
	v_writelane_b32 v254, s11, 21
	s_add_u32 s14, s40, 0x4200
	v_writelane_b32 v254, s0, 22
	s_addc_u32 s15, s41, 0
	v_writelane_b32 v254, s14, 23
	s_waitcnt lgkmcnt(0)
	v_cvt_f32_ubyte0_e32 v0, s10
	v_rcp_iflag_f32_e32 v1, v0
	v_writelane_b32 v254, s15, 24
	s_add_u32 s14, s40, 0x7400
	s_addc_u32 s15, s41, 0
	v_writelane_b32 v254, s14, 25
	v_cvt_f32_ubyte0_e32 v2, s9
	v_mul_f32_e32 v1, v2, v1
	v_writelane_b32 v254, s15, 26
	s_add_u32 s14, s40, 0x7500
	s_addc_u32 s15, s41, 0
	v_writelane_b32 v254, s14, 27
	s_add_u32 s0, s40, 0x2000
	v_trunc_f32_e32 v1, v1
	v_writelane_b32 v254, s15, 28
	v_writelane_b32 v254, s0, 29
	s_addc_u32 s0, s41, 0
	s_cmpk_lt_i32 s2, 0xc0
	v_writelane_b32 v254, s0, 30
	s_cselect_b64 s[14:15], -1, 0
	v_writelane_b32 v254, s14, 31
	s_cmp_lt_i32 s13, 0
	v_cvt_u32_f32_e32 v3, v1
	v_writelane_b32 v254, s15, 32
	s_cselect_b64 s[14:15], -1, 0
	v_writelane_b32 v254, s14, 33
	s_cmpk_lt_u32 s13, 0x6c
	v_fma_f32 v1, -v1, v0, v2
	v_writelane_b32 v254, s15, 34
	s_cselect_b64 s[14:15], -1, 0
	v_writelane_b32 v254, s14, 35
	s_add_u32 s0, s40, 0x400000
	s_mov_b32 s97, 0
	v_writelane_b32 v254, s15, 36
	v_writelane_b32 v254, s0, 37
	s_addc_u32 s0, s41, 0
	v_writelane_b32 v254, s0, 38
	s_add_u32 s0, s40, 0x300000
	v_writelane_b32 v254, s0, 39
	s_addc_u32 s0, s41, 0
	s_cmpk_lt_i32 s2, 0x300
	v_writelane_b32 v254, s0, 40
	s_cselect_b64 s[14:15], -1, 0
	v_writelane_b32 v254, s14, 41
	s_lshl_b32 s0, s13, 3
	v_mov_b32_e32 v65, 0
	v_writelane_b32 v254, s15, 42
	v_writelane_b32 v254, s0, 43
	s_add_u32 s0, s40, 0x4600000
	v_writelane_b32 v254, s0, 44
	s_addc_u32 s0, s41, 0
	v_writelane_b32 v254, s0, 45
	s_add_u32 s0, s40, 0x2600000
	v_writelane_b32 v254, s0, 46
	s_addc_u32 s0, s41, 0
	v_writelane_b32 v254, s0, 47
	s_add_u32 s0, s40, 0x1e00000
	v_writelane_b32 v254, s0, 48
	s_addc_u32 s0, s41, 0
	v_writelane_b32 v254, s0, 49
	s_add_u32 s0, s40, 0x800000
	v_writelane_b32 v254, s0, 50
	s_addc_u32 s0, s41, 0
	v_writelane_b32 v254, s0, 51
	s_add_i32 s0, s2, 0xfffffe00
	s_cmp_gt_u32 s0, 0xffffff5f
	s_mul_i32 s0, s1, s6
	s_cselect_b64 s[14:15], -1, 0
	s_add_i32 s0, s0, s4
	s_ashr_i32 s5, s0, 31
	s_lshr_b32 s5, s5, 27
	s_add_i32 s5, s0, s5
	s_ashr_i32 s6, s5, 5
	s_and_b32 s5, s5, 0xffe0
	s_sub_i32 s5, s0, s5
	s_bfe_i32 s0, s5, 0x80000
	s_bfe_u32 s0, s0, 0x3000c
	s_add_i32 s11, s5, s0
	s_mul_i32 s1, s1, s7
	s_bfe_i32 s0, s11, 0x80000
	s_and_b32 s11, s11, 0xf8
	s_add_i32 s1, s1, s4
	s_sub_i32 s5, s5, s11
	s_ashr_i32 s4, s1, 31
	v_writelane_b32 v254, s14, 52
	s_lshl_b32 s6, s6, 3
	s_sext_i32_i16 s12, s0
	s_sext_i32_i8 s5, s5
	s_lshr_b32 s4, s4, 25
	v_writelane_b32 v254, s15, 53
	s_add_i32 s14, s6, s5
	s_ashr_i32 s5, s12, 3
	s_add_i32 s4, s1, s4
	v_writelane_b32 v254, s5, 54
	s_ashr_i32 s5, s4, 7
	s_and_b32 s4, s4, 0xff80
	s_sub_i32 s1, s1, s4
	s_bfe_i32 s4, s1, 0x80000
	s_bfe_u32 s4, s4, 0x3000c
	s_add_i32 s6, s1, s4
	s_bfe_i32 s4, s6, 0x80000
	s_and_b32 s6, s6, 0xf8
	s_sub_i32 s1, s1, s6
	s_lshl_b32 s5, s5, 3
	s_sext_i32_i16 s7, s4
	s_sext_i32_i8 s1, s1
	s_add_i32 s16, s5, s1
	s_ashr_i32 s1, s7, 3
	v_writelane_b32 v254, s1, 55
	s_mov_b32 s6, s16
	s_lshr_b32 s4, s7, 3
	s_ashr_i32 s17, s16, 31
	v_writelane_b32 v254, s6, 56
	s_bfe_i64 s[4:5], s[4:5], 0x100000
	s_lshl_b64 s[4:5], s[4:5], 19
	v_writelane_b32 v254, s7, 57
	s_lshl_b64 s[6:7], s[16:17], 19
	v_writelane_b32 v254, s6, 58
	s_ashr_i32 s15, s14, 31
	s_lshr_b32 s0, s12, 3
	v_writelane_b32 v254, s7, 59
	v_writelane_b32 v254, s4, 60
	s_bfe_i64 s[0:1], s[0:1], 0x100000
	v_mov_b32_e32 v229, 0x358637bd
	v_writelane_b32 v254, s5, 61
	s_lshl_b64 s[4:5], s[14:15], 19
	v_writelane_b32 v254, s4, 62
	v_mov_b32_e32 v230, 1
	v_mov_b32_e32 v190, 0x3f4ccccd
	v_writelane_b32 v254, s5, 63
	s_lshl_b64 s[4:5], s[0:1], 19
	v_writelane_b32 v255, s4, 0
	s_lshl_b64 s[0:1], s[0:1], 21
	v_mov_b32_e32 v231, 0x1000
	v_writelane_b32 v255, s5, 1
	s_mov_b32 s4, s14
	v_writelane_b32 v255, s4, 2
	v_mov_b32_e32 v232, 0x3ecc95a3
	v_mov_b32_e32 v233, 0x3c088889
	v_writelane_b32 v255, s5, 3
	s_lshl_b64 s[4:5], s[14:15], 21
	v_writelane_b32 v255, s4, 4
	v_mov_b32_e32 v234, 0x7f800000
	v_mov_b32_e32 v235, 0x7fc00000
	v_writelane_b32 v255, s5, 5
	v_writelane_b32 v255, s0, 6
	v_readfirstlane_b32 s4, v3
	v_mov_b32_e32 v236, 0xff800000
	v_writelane_b32 v255, s1, 7
	v_cmp_ge_f32_e64 s[0:1], |v1|, v0
	s_cmp_lg_u64 s[0:1], 0
	s_addc_u32 s0, s4, 0
	s_mul_i32 s1, s0, s10
	s_sub_i32 s1, s9, s1
	s_add_i32 s1, s1, s8
	s_and_b32 s1, s1, 0xff
	s_and_b32 s4, s0, 0xff
	s_cmp_gt_u32 s4, 7
	v_writelane_b32 v255, s1, 8
	s_cselect_b64 s[0:1], -1, 0
	s_cmp_lg_u64 s[0:1], 0
	s_addc_u32 s0, s4, 0
	s_load_dwordx8 s[4:11], s[80:81], 0xd0
	v_writelane_b32 v255, s0, 9
	v_writelane_b32 v255, s13, 10
	s_lshl_b32 s0, s13, 6
	v_writelane_b32 v255, s0, 11
	s_addk_i32 s0, 0xf500
	s_lshl_b32 s79, s63, 6
	s_waitcnt lgkmcnt(0)
	s_mov_b64 s[4:5], s[8:9]
	v_writelane_b32 v255, s0, 12
	s_add_u32 s0, s4, 0x1000000
	s_addc_u32 s1, s5, 0
	v_writelane_b32 v255, s0, 13
	v_mov_b32_e32 v237, 0x3e800000
	v_bfrev_b32_e32 v238, 0.5
	v_writelane_b32 v255, s1, 14
	s_load_dwordx2 s[0:1], s[80:81], 0x68
	v_mov_b64_e32 v[192:193], 0xc0
	v_mov_b64_e32 v[194:195], 0xbf
	v_not_b32_e32 v239, 30
	s_mov_b32 s55, 0x800000
	s_waitcnt lgkmcnt(0)
	s_add_u32 s0, s0, 0xb00000
	s_addc_u32 s1, s1, 0
	v_writelane_b32 v255, s0, 15
	s_movk_i32 s92, 0x3ff
	s_movk_i32 s93, 0x1600
	v_writelane_b32 v255, s1, 16
	s_add_i32 s0, 0, 0x20020
	v_writelane_b32 v255, s0, 17
	s_add_i32 s0, 0, 0x20024
	v_writelane_b32 v255, s0, 18
	s_add_i32 s0, 0, 0x12200
	v_writelane_b32 v255, s0, 19
	s_add_i32 s0, 0, 0x15800
	v_writelane_b32 v255, s0, 20
	s_brev_b32 s0, 1
	v_writelane_b32 v255, s0, 21
	s_movk_i32 s94, 0x90
	s_movk_i32 s95, 0xf7
	v_writelane_b32 v255, s1, 22
	v_writelane_b32 v255, s2, 23
	v_writelane_b32 v255, s3, 24
	v_writelane_b32 v255, s80, 25
	s_movk_i32 s46, 0x7d0
	s_add_i32 s47, 0, 0x20000
	v_writelane_b32 v255, s81, 26
	v_writelane_b32 v255, s63, 27
	v_writelane_b32 v255, s79, 28
	s_mov_b32 s52, 0x41000000
	s_movk_i32 s54, 0xfeff
	s_mov_b32 s64, 0xc800
	s_mov_b32 s65, 0xbe800000
	s_movk_i32 s78, 0x2c00
	s_mov_b64 s[28:29], 0
	s_mov_b64 s[30:31], 0x80
	s_mov_b64 s[72:73], 0
	s_mov_b32 s74, s97
	s_and_b32 s58, s2, 7
	s_lshr_b32 s59, s2, 3
	s_mul_i32 s60, s59, 43
	s_lshr_b32 s60, s60, 8
	s_mul_i32 s61, s60, 6
	s_sub_i32 s59, s59, s61
	s_lshl_b32 s61, s58, 1
	s_add_i32 s61, s61, s59
	s_lshl_b32 s58, s58, 2
	s_add_i32 s58, s58, s59
	s_add_i32 s58, s58, 14
	s_cmp_lt_u32 s59, 2
	s_cselect_b32 s58, s61, s58
	s_mov_b32 s61, 0
	v_writelane_b32 v254, s60, 54
	v_writelane_b32 v254, s60, 55
	v_writelane_b32 v254, s58, 56
	v_writelane_b32 v254, s61, 57
	v_writelane_b32 v255, s58, 2
	v_writelane_b32 v255, s61, 3
	v_writelane_b32 v254, s61, 59
	v_writelane_b32 v254, s61, 61
	v_writelane_b32 v254, s61, 63
	v_writelane_b32 v255, s61, 1
	v_writelane_b32 v255, s61, 5
	v_writelane_b32 v255, s61, 7
	s_lshl_b32 s59, s58, 19
	v_writelane_b32 v254, s59, 58
	v_writelane_b32 v254, s59, 62
	s_lshl_b32 s59, s58, 21
	v_writelane_b32 v255, s59, 4
	s_lshl_b32 s59, s60, 19
	v_writelane_b32 v254, s59, 60
	v_writelane_b32 v255, s59, 0
	s_lshl_b32 s59, s60, 21
	v_writelane_b32 v255, s59, 6
	s_and_b32 s58, s2, 7
	s_lshr_b32 s59, s2, 3
	s_mul_i32 s61, s59, 43
	s_lshr_b32 s61, s61, 8
	s_mul_i32 s60, s61, 6
	s_sub_i32 s60, s59, s60
	s_cmp_lt_u32 s59, 30
	s_cbranch_scc1 .Lmy_h_rc
	s_movk_i32 s61, 5
	s_sub_i32 s60, s59, 30
.Lmy_h_rc:
	s_lshl_b32 s59, s58, 1
	s_add_i32 s59, s59, s60
	s_lshl_b32 s58, s58, 2
	s_add_i32 s58, s58, s60
	s_add_i32 s58, s58, 14
	s_cmp_lt_u32 s60, 2
	s_cselect_b32 s60, s59, s58

.LBB0_463:
	s_add_i32 s63, s63, 1
	s_mul_i32 s1, s63, s51
	s_mul_hi_u32 s4, s63, s42
	s_add_i32 s4, s4, s1
	s_mul_i32 s1, s63, s42
	s_add_u32 s56, s1, s2
	s_addc_u32 s57, s4, s43
	v_mov_b64_e32 v[0:1], 0x200
	v_cmp_lt_i64_e64 s[4:5], s[56:57], v[0:1]
	v_mov_b64_e32 v[0:1], 0x1ff
	v_cmp_gt_i64_e32 vcc, s[56:57], v[0:1]
	s_cbranch_vccnz .LBB0_468
	s_and_b32 s1, s56, 7
	s_lshr_b32 s13, s56, 3
	s_and_b32 s13, s13, 31
	s_cmp_lt_u32 s13, 4
	s_cbranch_scc0 .Lmy_in_b
	s_movk_i32 s24, 5
	s_add_i32 s22, s13, 2
	s_branch .Lmy_in_rc
.Lmy_in_b:
	s_cmp_lt_u32 s13, 16
	s_cbranch_scc0 .Lmy_in_c
	s_sub_i32 s13, s13, 4
	s_mul_i32 s24, s13, 43
	s_lshr_b32 s24, s24, 8
	s_mul_i32 s22, s24, 6
	s_sub_i32 s22, s13, s22
	s_add_i32 s24, s24, 6
	s_branch .Lmy_in_rc
.Lmy_in_c:
	s_cmp_lt_u32 s13, 20
	s_cbranch_scc0 .Lmy_in_d
	s_movk_i32 s24, 8
	s_sub_i32 s22, s13, 14
	s_branch .Lmy_in_rc
.Lmy_in_d:
	s_sub_i32 s13, s13, 20
	s_mul_i32 s24, s13, 43
	s_lshr_b32 s24, s24, 8
	s_mul_i32 s22, s24, 6
	s_sub_i32 s22, s13, s22
	s_add_i32 s24, s24, 9
.Lmy_in_rc:
	s_lshl_b32 s13, s1, 1
	s_add_i32 s13, s13, s22
	s_lshl_b32 s1, s1, 2
	s_add_i32 s1, s1, s22
	s_add_i32 s1, s1, 14
	s_cmp_lt_u32 s22, 2
	s_cselect_b32 s22, s13, s1
